# phase-0 adaLN item: silu(c) staging loop issues 8 loads per round trip instead of 1 (32 serialized global-load waits -> 4)
# speedup vs baseline: 1.0100x; 1.0100x over previous
; DI float sigmoidf_(float x) { return frcp(1.0f + fexp2(-x * LOG2E)); }
; DI void phase_prep(KargPtr p, unsigned char* smem) {
;     ...
;             float* cond = fs;
;             float* red = fs + 8192;
;             for (int e = tid; e < 8192; e += 256) { const float cv = p->c[e]; cond[e] = cv * sigmoidf_(cv); }
;             __syncthreads();
.LBB0_19:
	s_mov_b32 s20, 4
.Lcond_loop:
	v_add_co_u32_e32 v232, vcc, 0x1000, v2
	s_nop 1
	v_addc_co_u32_e32 v233, vcc, 0, v3, vcc
	global_load_dword v224, v[2:3], off
	global_load_dword v225, v[2:3], off offset:1024
	global_load_dword v226, v[2:3], off offset:2048
	global_load_dword v227, v[2:3], off offset:3072
	global_load_dword v228, v[232:233], off
	global_load_dword v229, v[232:233], off offset:1024
	global_load_dword v230, v[232:233], off offset:2048
	global_load_dword v231, v[232:233], off offset:3072
	v_add_co_u32_e32 v2, vcc, 0x2000, v2
	s_nop 1
	v_addc_co_u32_e32 v3, vcc, 0, v3, vcc
	s_waitcnt vmcnt(0)
	v_mul_f32_e32 v7, 0xbfb8aa3b, v224
	v_exp_f32_e32 v7, v7
	s_nop 0
	v_add_f32_e32 v7, 1.0, v7
	v_rcp_f32_e32 v7, v7
	s_nop 0
	v_mul_f32_e32 v6, v224, v7
	ds_write_b32 v4, v6
	v_mul_f32_e32 v7, 0xbfb8aa3b, v225
	v_exp_f32_e32 v7, v7
	s_nop 0
	v_add_f32_e32 v7, 1.0, v7
	v_rcp_f32_e32 v7, v7
	s_nop 0
	v_mul_f32_e32 v6, v225, v7
	ds_write_b32 v4, v6 offset:1024
	v_mul_f32_e32 v7, 0xbfb8aa3b, v226
	v_exp_f32_e32 v7, v7
	s_nop 0
	v_add_f32_e32 v7, 1.0, v7
	v_rcp_f32_e32 v7, v7
	s_nop 0
	v_mul_f32_e32 v6, v226, v7
	ds_write_b32 v4, v6 offset:2048
	v_mul_f32_e32 v7, 0xbfb8aa3b, v227
	v_exp_f32_e32 v7, v7
	s_nop 0
	v_add_f32_e32 v7, 1.0, v7
	v_rcp_f32_e32 v7, v7
	s_nop 0
	v_mul_f32_e32 v6, v227, v7
	ds_write_b32 v4, v6 offset:3072
	v_mul_f32_e32 v7, 0xbfb8aa3b, v228
	v_exp_f32_e32 v7, v7
	s_nop 0
	v_add_f32_e32 v7, 1.0, v7
	v_rcp_f32_e32 v7, v7
	s_nop 0
	v_mul_f32_e32 v6, v228, v7
	ds_write_b32 v4, v6 offset:4096
	v_mul_f32_e32 v7, 0xbfb8aa3b, v229
	v_exp_f32_e32 v7, v7
	s_nop 0
	v_add_f32_e32 v7, 1.0, v7
	v_rcp_f32_e32 v7, v7
	s_nop 0
	v_mul_f32_e32 v6, v229, v7
	ds_write_b32 v4, v6 offset:5120
	v_mul_f32_e32 v7, 0xbfb8aa3b, v230
	v_exp_f32_e32 v7, v7
	s_nop 0
	v_add_f32_e32 v7, 1.0, v7
	v_rcp_f32_e32 v7, v7
	s_nop 0
	v_mul_f32_e32 v6, v230, v7
	ds_write_b32 v4, v6 offset:6144
	v_mul_f32_e32 v7, 0xbfb8aa3b, v231
	v_exp_f32_e32 v7, v7
	s_nop 0
	v_add_f32_e32 v7, 1.0, v7
	v_rcp_f32_e32 v7, v7
	s_nop 0
	v_mul_f32_e32 v6, v231, v7
	ds_write_b32 v4, v6 offset:7168
	v_add_u32_e32 v4, 0x2000, v4
	s_sub_i32 s20, s20, 1
	s_cmp_lg_u32 s20, 0
	s_cbranch_scc1 .Lcond_loop
